# cache-policy hints (streaming): non-temporal output stores in the conv fast path plus non-temporal ax loads in the lru fast path
# speedup vs baseline: 1.0094x; 1.0094x over previous
; DI u32x4 pack8(const float (&f)[8]) { u32x4 w; w.x = pk2(f[0], f[1]); w.y = pk2(f[2], f[3]); w.z = pk2(f[4], f[5]); w.w = pk2(f[6], f[7]); return w; }
; DI void phase_conv(const Params& p) {
;     ...
;         for (int r = 0; r < 11; ++r) raw[r] = (r >= 3 || t0 > 0) ? *(const u32x4*)(big + (size_t)(tok0 - 3 + r) * 4096 + ch) : (u32x4){0u, 0u, 0u, 0u};
; #pragma unroll
;         for (int o = 0; o < 8; ++o) {
;             float acc[8];
; #pragma unroll
;             for (int e = 0; e < 8; ++e) acc[e] = bs[e];
; #pragma unroll
;             for (int jx = 0; jx < 4; ++jx) { float f[8]; unpack8(raw[o + jx], f);
; #pragma unroll
;                 for (int e = 0; e < 8; ++e) acc[e] += f[e] * wv[jx][e]; }
;             *(u32x4*)(xc + (size_t)(tok0 + o) * DM + ch) = pack8(acc);
.Lcv_nopad0:
	s_mov_b64 s[44:45], s[28:29]
	v_lshlrev_b32_e32 v88, 16, v0
	v_and_b32_e32 v89, 0xffff0000, v0
	v_lshlrev_b32_e32 v90, 16, v1
	v_and_b32_e32 v91, 0xffff0000, v1
	v_lshlrev_b32_e32 v92, 16, v2
	v_and_b32_e32 v93, 0xffff0000, v2
	v_lshlrev_b32_e32 v94, 16, v3
	v_and_b32_e32 v95, 0xffff0000, v3
	v_pk_fma_f32 v[96:97], v[88:89], v[232:233], v[206:207]
	v_pk_fma_f32 v[98:99], v[90:91], v[234:235], v[208:209]
	v_pk_fma_f32 v[100:101], v[92:93], v[236:237], v[210:211]
	v_pk_fma_f32 v[102:103], v[94:95], v[238:239], v[212:213]
	v_lshlrev_b32_e32 v88, 16, v4
	v_and_b32_e32 v89, 0xffff0000, v4
	v_lshlrev_b32_e32 v90, 16, v5
	v_and_b32_e32 v91, 0xffff0000, v5
	v_lshlrev_b32_e32 v92, 16, v6
	v_and_b32_e32 v93, 0xffff0000, v6
	v_lshlrev_b32_e32 v94, 16, v7
	v_and_b32_e32 v95, 0xffff0000, v7
	v_pk_fma_f32 v[96:97], v[88:89], v[240:241], v[96:97]
	v_pk_fma_f32 v[98:99], v[90:91], v[242:243], v[98:99]
	v_pk_fma_f32 v[100:101], v[92:93], v[244:245], v[100:101]
	v_pk_fma_f32 v[102:103], v[94:95], v[246:247], v[102:103]
	v_pk_fma_f32 v[104:105], v[88:89], v[232:233], v[206:207]
	v_pk_fma_f32 v[106:107], v[90:91], v[234:235], v[208:209]
	v_pk_fma_f32 v[108:109], v[92:93], v[236:237], v[210:211]
	v_pk_fma_f32 v[110:111], v[94:95], v[238:239], v[212:213]
	v_lshlrev_b32_e32 v88, 16, v8
	v_and_b32_e32 v89, 0xffff0000, v8
	v_lshlrev_b32_e32 v90, 16, v9
	v_and_b32_e32 v91, 0xffff0000, v9
	v_lshlrev_b32_e32 v92, 16, v10
	v_and_b32_e32 v93, 0xffff0000, v10
	v_lshlrev_b32_e32 v94, 16, v11
	v_and_b32_e32 v95, 0xffff0000, v11
	v_pk_fma_f32 v[96:97], v[88:89], v[248:249], v[96:97]
	v_pk_fma_f32 v[98:99], v[90:91], v[250:251], v[98:99]
	v_pk_fma_f32 v[100:101], v[92:93], v[252:253], v[100:101]
	v_pk_fma_f32 v[102:103], v[94:95], v[254:255], v[102:103]
	v_pk_fma_f32 v[104:105], v[88:89], v[240:241], v[104:105]
	v_pk_fma_f32 v[106:107], v[90:91], v[242:243], v[106:107]
	v_pk_fma_f32 v[108:109], v[92:93], v[244:245], v[108:109]
	v_pk_fma_f32 v[110:111], v[94:95], v[246:247], v[110:111]
	v_pk_fma_f32 v[112:113], v[88:89], v[232:233], v[206:207]
	v_pk_fma_f32 v[114:115], v[90:91], v[234:235], v[208:209]
	v_pk_fma_f32 v[116:117], v[92:93], v[236:237], v[210:211]
	v_pk_fma_f32 v[118:119], v[94:95], v[238:239], v[212:213]
	v_lshlrev_b32_e32 v88, 16, v12
	v_and_b32_e32 v89, 0xffff0000, v12
	v_lshlrev_b32_e32 v90, 16, v13
	v_and_b32_e32 v91, 0xffff0000, v13
	v_lshlrev_b32_e32 v92, 16, v14
	v_and_b32_e32 v93, 0xffff0000, v14
	v_lshlrev_b32_e32 v94, 16, v15
	v_and_b32_e32 v95, 0xffff0000, v15
	v_pk_fma_f32 v[96:97], v[88:89], v[198:199], v[96:97]
	v_pk_fma_f32 v[98:99], v[90:91], v[200:201], v[98:99]
	v_pk_fma_f32 v[100:101], v[92:93], v[202:203], v[100:101]
	v_pk_fma_f32 v[102:103], v[94:95], v[204:205], v[102:103]
	v_pk_fma_f32 v[104:105], v[88:89], v[248:249], v[104:105]
	v_pk_fma_f32 v[106:107], v[90:91], v[250:251], v[106:107]
	v_pk_fma_f32 v[108:109], v[92:93], v[252:253], v[108:109]
	v_pk_fma_f32 v[110:111], v[94:95], v[254:255], v[110:111]
	v_pk_fma_f32 v[112:113], v[88:89], v[240:241], v[112:113]
	v_pk_fma_f32 v[114:115], v[90:91], v[242:243], v[114:115]
	v_pk_fma_f32 v[116:117], v[92:93], v[244:245], v[116:117]
	v_pk_fma_f32 v[118:119], v[94:95], v[246:247], v[118:119]
	v_pk_fma_f32 v[120:121], v[88:89], v[232:233], v[206:207]
	v_pk_fma_f32 v[122:123], v[90:91], v[234:235], v[208:209]
	v_pk_fma_f32 v[124:125], v[92:93], v[236:237], v[210:211]
	v_pk_fma_f32 v[126:127], v[94:95], v[238:239], v[212:213]
	v_cvt_pk_bf16_f32 v164, v96, v97
	v_cvt_pk_bf16_f32 v165, v98, v99
	v_cvt_pk_bf16_f32 v166, v100, v101
	v_cvt_pk_bf16_f32 v167, v102, v103
	global_store_dwordx4 v161, v[164:167], s[44:45] nt
	s_add_u32 s44, s44, 0x1000
	s_addc_u32 s45, s45, 0
	s_nop 1
	v_lshlrev_b32_e32 v88, 16, v16
	v_and_b32_e32 v89, 0xffff0000, v16
	v_lshlrev_b32_e32 v90, 16, v17
	v_and_b32_e32 v91, 0xffff0000, v17
	v_lshlrev_b32_e32 v92, 16, v18
	v_and_b32_e32 v93, 0xffff0000, v18
	v_lshlrev_b32_e32 v94, 16, v19
	v_and_b32_e32 v95, 0xffff0000, v19
	v_pk_fma_f32 v[104:105], v[88:89], v[198:199], v[104:105]
	v_pk_fma_f32 v[106:107], v[90:91], v[200:201], v[106:107]
	v_pk_fma_f32 v[108:109], v[92:93], v[202:203], v[108:109]
	v_pk_fma_f32 v[110:111], v[94:95], v[204:205], v[110:111]
	v_pk_fma_f32 v[112:113], v[88:89], v[248:249], v[112:113]
	v_pk_fma_f32 v[114:115], v[90:91], v[250:251], v[114:115]
	v_pk_fma_f32 v[116:117], v[92:93], v[252:253], v[116:117]
	v_pk_fma_f32 v[118:119], v[94:95], v[254:255], v[118:119]
	v_pk_fma_f32 v[120:121], v[88:89], v[240:241], v[120:121]
	v_pk_fma_f32 v[122:123], v[90:91], v[242:243], v[122:123]
	v_pk_fma_f32 v[124:125], v[92:93], v[244:245], v[124:125]
	v_pk_fma_f32 v[126:127], v[94:95], v[246:247], v[126:127]
	v_pk_fma_f32 v[128:129], v[88:89], v[232:233], v[206:207]
	v_pk_fma_f32 v[130:131], v[90:91], v[234:235], v[208:209]
	v_pk_fma_f32 v[132:133], v[92:93], v[236:237], v[210:211]
	v_pk_fma_f32 v[134:135], v[94:95], v[238:239], v[212:213]
	v_cvt_pk_bf16_f32 v164, v104, v105
	v_cvt_pk_bf16_f32 v165, v106, v107
	v_cvt_pk_bf16_f32 v166, v108, v109
	v_cvt_pk_bf16_f32 v167, v110, v111
	global_store_dwordx4 v161, v[164:167], s[44:45] nt
	s_add_u32 s44, s44, 0x1000
	s_addc_u32 s45, s45, 0
	s_nop 1
	v_lshlrev_b32_e32 v88, 16, v20
	v_and_b32_e32 v89, 0xffff0000, v20
	v_lshlrev_b32_e32 v90, 16, v21
	v_and_b32_e32 v91, 0xffff0000, v21
	v_lshlrev_b32_e32 v92, 16, v22
	v_and_b32_e32 v93, 0xffff0000, v22
	v_lshlrev_b32_e32 v94, 16, v23
	v_and_b32_e32 v95, 0xffff0000, v23
	v_pk_fma_f32 v[112:113], v[88:89], v[198:199], v[112:113]
	v_pk_fma_f32 v[114:115], v[90:91], v[200:201], v[114:115]
	v_pk_fma_f32 v[116:117], v[92:93], v[202:203], v[116:117]
; DI u32x4 pack8(const float (&f)[8]) { u32x4 w; w.x = pk2(f[0], f[1]); w.y = pk2(f[2], f[3]); w.z = pk2(f[4], f[5]); w.w = pk2(f[6], f[7]); return w; }
; DI void phase_conv(const Params& p) {
;     ...
;         for (int o = 0; o < 8; ++o) {
;             float acc[8];
; #pragma unroll
;             for (int e = 0; e < 8; ++e) acc[e] = bs[e];
; #pragma unroll
;             for (int jx = 0; jx < 4; ++jx) { float f[8]; unpack8(raw[o + jx], f);
; #pragma unroll
;                 for (int e = 0; e < 8; ++e) acc[e] += f[e] * wv[jx][e]; }
;             *(u32x4*)(xc + (size_t)(tok0 + o) * DM + ch) = pack8(acc);
	v_pk_fma_f32 v[118:119], v[94:95], v[204:205], v[118:119]
	v_pk_fma_f32 v[120:121], v[88:89], v[248:249], v[120:121]
	v_pk_fma_f32 v[122:123], v[90:91], v[250:251], v[122:123]
	v_pk_fma_f32 v[124:125], v[92:93], v[252:253], v[124:125]
	v_pk_fma_f32 v[126:127], v[94:95], v[254:255], v[126:127]
	v_pk_fma_f32 v[128:129], v[88:89], v[240:241], v[128:129]
	v_pk_fma_f32 v[130:131], v[90:91], v[242:243], v[130:131]
	v_pk_fma_f32 v[132:133], v[92:93], v[244:245], v[132:133]
	v_pk_fma_f32 v[134:135], v[94:95], v[246:247], v[134:135]
	v_pk_fma_f32 v[136:137], v[88:89], v[232:233], v[206:207]
	v_pk_fma_f32 v[138:139], v[90:91], v[234:235], v[208:209]
	v_pk_fma_f32 v[140:141], v[92:93], v[236:237], v[210:211]
	v_pk_fma_f32 v[142:143], v[94:95], v[238:239], v[212:213]
	v_cvt_pk_bf16_f32 v164, v112, v113
	v_cvt_pk_bf16_f32 v165, v114, v115
	v_cvt_pk_bf16_f32 v166, v116, v117
	v_cvt_pk_bf16_f32 v167, v118, v119
	global_store_dwordx4 v161, v[164:167], s[44:45] nt
	s_add_u32 s44, s44, 0x1000
	s_addc_u32 s45, s45, 0
	s_nop 1
	v_lshlrev_b32_e32 v88, 16, v24
	v_and_b32_e32 v89, 0xffff0000, v24
	v_lshlrev_b32_e32 v90, 16, v25
	v_and_b32_e32 v91, 0xffff0000, v25
	v_lshlrev_b32_e32 v92, 16, v26
	v_and_b32_e32 v93, 0xffff0000, v26
	v_lshlrev_b32_e32 v94, 16, v27
	v_and_b32_e32 v95, 0xffff0000, v27
	v_pk_fma_f32 v[120:121], v[88:89], v[198:199], v[120:121]
	v_pk_fma_f32 v[122:123], v[90:91], v[200:201], v[122:123]
	v_pk_fma_f32 v[124:125], v[92:93], v[202:203], v[124:125]
	v_pk_fma_f32 v[126:127], v[94:95], v[204:205], v[126:127]
	v_pk_fma_f32 v[128:129], v[88:89], v[248:249], v[128:129]
	v_pk_fma_f32 v[130:131], v[90:91], v[250:251], v[130:131]
	v_pk_fma_f32 v[132:133], v[92:93], v[252:253], v[132:133]
	v_pk_fma_f32 v[134:135], v[94:95], v[254:255], v[134:135]
	v_pk_fma_f32 v[136:137], v[88:89], v[240:241], v[136:137]
	v_pk_fma_f32 v[138:139], v[90:91], v[242:243], v[138:139]
	v_pk_fma_f32 v[140:141], v[92:93], v[244:245], v[140:141]
	v_pk_fma_f32 v[142:143], v[94:95], v[246:247], v[142:143]
	v_pk_fma_f32 v[144:145], v[88:89], v[232:233], v[206:207]
	v_pk_fma_f32 v[146:147], v[90:91], v[234:235], v[208:209]
	v_pk_fma_f32 v[148:149], v[92:93], v[236:237], v[210:211]
	v_pk_fma_f32 v[150:151], v[94:95], v[238:239], v[212:213]
	v_cvt_pk_bf16_f32 v164, v120, v121
	v_cvt_pk_bf16_f32 v165, v122, v123
	v_cvt_pk_bf16_f32 v166, v124, v125
	v_cvt_pk_bf16_f32 v167, v126, v127
	global_store_dwordx4 v161, v[164:167], s[44:45] nt
	s_add_u32 s44, s44, 0x1000
	s_addc_u32 s45, s45, 0
	s_nop 1
	v_lshlrev_b32_e32 v88, 16, v28
	v_and_b32_e32 v89, 0xffff0000, v28
	v_lshlrev_b32_e32 v90, 16, v29
	v_and_b32_e32 v91, 0xffff0000, v29
	v_lshlrev_b32_e32 v92, 16, v30
	v_and_b32_e32 v93, 0xffff0000, v30
	v_lshlrev_b32_e32 v94, 16, v31
	v_and_b32_e32 v95, 0xffff0000, v31
	v_pk_fma_f32 v[128:129], v[88:89], v[198:199], v[128:129]
	v_pk_fma_f32 v[130:131], v[90:91], v[200:201], v[130:131]
	v_pk_fma_f32 v[132:133], v[92:93], v[202:203], v[132:133]
	v_pk_fma_f32 v[134:135], v[94:95], v[204:205], v[134:135]
	v_pk_fma_f32 v[136:137], v[88:89], v[248:249], v[136:137]
	v_pk_fma_f32 v[138:139], v[90:91], v[250:251], v[138:139]
	v_pk_fma_f32 v[140:141], v[92:93], v[252:253], v[140:141]
	v_pk_fma_f32 v[142:143], v[94:95], v[254:255], v[142:143]
	v_pk_fma_f32 v[144:145], v[88:89], v[240:241], v[144:145]
	v_pk_fma_f32 v[146:147], v[90:91], v[242:243], v[146:147]
	v_pk_fma_f32 v[148:149], v[92:93], v[244:245], v[148:149]
	v_pk_fma_f32 v[150:151], v[94:95], v[246:247], v[150:151]
	v_pk_fma_f32 v[152:153], v[88:89], v[232:233], v[206:207]
	v_pk_fma_f32 v[154:155], v[90:91], v[234:235], v[208:209]
	v_pk_fma_f32 v[156:157], v[92:93], v[236:237], v[210:211]
	v_pk_fma_f32 v[158:159], v[94:95], v[238:239], v[212:213]
	v_cvt_pk_bf16_f32 v164, v128, v129
	v_cvt_pk_bf16_f32 v165, v130, v131
	v_cvt_pk_bf16_f32 v166, v132, v133
	v_cvt_pk_bf16_f32 v167, v134, v135
	global_store_dwordx4 v161, v[164:167], s[44:45] nt
	s_add_u32 s44, s44, 0x1000
	s_addc_u32 s45, s45, 0
	s_nop 1
	v_lshlrev_b32_e32 v88, 16, v32
	v_and_b32_e32 v89, 0xffff0000, v32
	v_lshlrev_b32_e32 v90, 16, v33
	v_and_b32_e32 v91, 0xffff0000, v33
	v_lshlrev_b32_e32 v92, 16, v34
	v_and_b32_e32 v93, 0xffff0000, v34
	v_lshlrev_b32_e32 v94, 16, v35
	v_and_b32_e32 v95, 0xffff0000, v35
	v_pk_fma_f32 v[136:137], v[88:89], v[198:199], v[136:137]
	v_pk_fma_f32 v[138:139], v[90:91], v[200:201], v[138:139]
	v_pk_fma_f32 v[140:141], v[92:93], v[202:203], v[140:141]
	v_pk_fma_f32 v[142:143], v[94:95], v[204:205], v[142:143]
	v_pk_fma_f32 v[144:145], v[88:89], v[248:249], v[144:145]
	v_pk_fma_f32 v[146:147], v[90:91], v[250:251], v[146:147]
	v_pk_fma_f32 v[148:149], v[92:93], v[252:253], v[148:149]
	v_pk_fma_f32 v[150:151], v[94:95], v[254:255], v[150:151]
	v_pk_fma_f32 v[152:153], v[88:89], v[240:241], v[152:153]
	v_pk_fma_f32 v[154:155], v[90:91], v[242:243], v[154:155]
	v_pk_fma_f32 v[156:157], v[92:93], v[244:245], v[156:157]
	v_pk_fma_f32 v[158:159], v[94:95], v[246:247], v[158:159]
	v_cvt_pk_bf16_f32 v164, v136, v137
	v_cvt_pk_bf16_f32 v165, v138, v139
	v_cvt_pk_bf16_f32 v166, v140, v141
	v_cvt_pk_bf16_f32 v167, v142, v143
	global_store_dwordx4 v161, v[164:167], s[44:45] nt
	s_add_u32 s44, s44, 0x1000
	s_addc_u32 s45, s45, 0
	s_nop 1
	v_lshlrev_b32_e32 v88, 16, v36
	v_and_b32_e32 v89, 0xffff0000, v36
	v_lshlrev_b32_e32 v90, 16, v37
	v_and_b32_e32 v91, 0xffff0000, v37
	v_lshlrev_b32_e32 v92, 16, v38
	v_and_b32_e32 v93, 0xffff0000, v38
	v_lshlrev_b32_e32 v94, 16, v39
	v_and_b32_e32 v95, 0xffff0000, v39
	v_pk_fma_f32 v[144:145], v[88:89], v[198:199], v[144:145]
	v_pk_fma_f32 v[146:147], v[90:91], v[200:201], v[146:147]
	v_pk_fma_f32 v[148:149], v[92:93], v[202:203], v[148:149]
; DI u32x4 pack8(const float (&f)[8]) { u32x4 w; w.x = pk2(f[0], f[1]); w.y = pk2(f[2], f[3]); w.z = pk2(f[4], f[5]); w.w = pk2(f[6], f[7]); return w; }
; DI void phase_conv(const Params& p) {
;     ...
;         for (int r = 0; r < 11; ++r) raw[r] = (r >= 3 || t0 > 0) ? *(const u32x4*)(big + (size_t)(tok0 - 3 + r) * 4096 + ch) : (u32x4){0u, 0u, 0u, 0u};
; #pragma unroll
;         for (int o = 0; o < 8; ++o) {
;             float acc[8];
; #pragma unroll
;             for (int e = 0; e < 8; ++e) acc[e] = bs[e];
; #pragma unroll
;             for (int jx = 0; jx < 4; ++jx) { float f[8]; unpack8(raw[o + jx], f);
; #pragma unroll
;                 for (int e = 0; e < 8; ++e) acc[e] += f[e] * wv[jx][e]; }
;             *(u32x4*)(xc + (size_t)(tok0 + o) * DM + ch) = pack8(acc);
	v_pk_fma_f32 v[150:151], v[94:95], v[204:205], v[150:151]
	v_pk_fma_f32 v[152:153], v[88:89], v[248:249], v[152:153]
	v_pk_fma_f32 v[154:155], v[90:91], v[250:251], v[154:155]
	v_pk_fma_f32 v[156:157], v[92:93], v[252:253], v[156:157]
	v_pk_fma_f32 v[158:159], v[94:95], v[254:255], v[158:159]
	v_cvt_pk_bf16_f32 v164, v144, v145
	v_cvt_pk_bf16_f32 v165, v146, v147
	v_cvt_pk_bf16_f32 v166, v148, v149
	v_cvt_pk_bf16_f32 v167, v150, v151
	global_store_dwordx4 v161, v[164:167], s[44:45] nt
	s_add_u32 s44, s44, 0x1000
	s_addc_u32 s45, s45, 0
	s_nop 1
	v_lshlrev_b32_e32 v88, 16, v40
	v_and_b32_e32 v89, 0xffff0000, v40
	v_lshlrev_b32_e32 v90, 16, v41
	v_and_b32_e32 v91, 0xffff0000, v41
	v_lshlrev_b32_e32 v92, 16, v42
	v_and_b32_e32 v93, 0xffff0000, v42
	v_lshlrev_b32_e32 v94, 16, v43
	v_and_b32_e32 v95, 0xffff0000, v43
	v_pk_fma_f32 v[152:153], v[88:89], v[198:199], v[152:153]
	v_pk_fma_f32 v[154:155], v[90:91], v[200:201], v[154:155]
	v_pk_fma_f32 v[156:157], v[92:93], v[202:203], v[156:157]
	v_pk_fma_f32 v[158:159], v[94:95], v[204:205], v[158:159]
	v_cvt_pk_bf16_f32 v164, v152, v153
	v_cvt_pk_bf16_f32 v165, v154, v155
	v_cvt_pk_bf16_f32 v166, v156, v157
	v_cvt_pk_bf16_f32 v167, v158, v159
	global_store_dwordx4 v161, v[164:167], s[44:45] nt
	s_add_u32 s44, s44, 0x1000
	s_addc_u32 s45, s45, 0
	s_nop 1
	s_add_u32 s28, s28, 0x1000000
	s_addc_u32 s29, s29, 0
	s_mov_b64 s[44:45], s[26:27]
	global_load_dwordx4 v[0:3], v160, s[44:45]
	s_add_u32 s44, s44, 0x2000
	s_addc_u32 s45, s45, 0
	global_load_dwordx4 v[4:7], v160, s[44:45]
	s_add_u32 s44, s44, 0x2000
	s_addc_u32 s45, s45, 0
	global_load_dwordx4 v[8:11], v160, s[44:45]
	s_add_u32 s44, s44, 0x2000
	s_addc_u32 s45, s45, 0
	global_load_dwordx4 v[12:15], v160, s[44:45]
	s_add_u32 s44, s44, 0x2000
	s_addc_u32 s45, s45, 0
	global_load_dwordx4 v[16:19], v160, s[44:45]
	s_add_u32 s44, s44, 0x2000
	s_addc_u32 s45, s45, 0
	global_load_dwordx4 v[20:23], v160, s[44:45]
	s_add_u32 s44, s44, 0x2000
	s_addc_u32 s45, s45, 0
	global_load_dwordx4 v[24:27], v160, s[44:45]
	s_add_u32 s44, s44, 0x2000
	s_addc_u32 s45, s45, 0
	global_load_dwordx4 v[28:31], v160, s[44:45]
	s_add_u32 s44, s44, 0x2000
	s_addc_u32 s45, s45, 0
	global_load_dwordx4 v[32:35], v160, s[44:45]
	s_add_u32 s44, s44, 0x2000
	s_addc_u32 s45, s45, 0
	global_load_dwordx4 v[36:39], v160, s[44:45]
	s_add_u32 s44, s44, 0x2000
	s_addc_u32 s45, s45, 0
	global_load_dwordx4 v[40:43], v160, s[44:45]
	s_add_u32 s26, s26, 0x2000000
	s_addc_u32 s27, s27, 0
	s_waitcnt vmcnt(19)
	s_cmp_eq_u32 s40, 0
	s_cbranch_scc0 .Lcv_nopad1
	v_mov_b32_e32 v44, 0
	v_mov_b32_e32 v45, 0
	v_mov_b32_e32 v46, 0
	v_mov_b32_e32 v47, 0
	v_mov_b32_e32 v48, 0
	v_mov_b32_e32 v49, 0
	v_mov_b32_e32 v50, 0
	v_mov_b32_e32 v51, 0
	v_mov_b32_e32 v52, 0
	v_mov_b32_e32 v53, 0
	v_mov_b32_e32 v54, 0
	v_mov_b32_e32 v55, 0
.Lcv_nopad1:
	s_mov_b64 s[44:45], s[28:29]
	v_lshlrev_b32_e32 v88, 16, v44
	v_and_b32_e32 v89, 0xffff0000, v44
	v_lshlrev_b32_e32 v90, 16, v45
	v_and_b32_e32 v91, 0xffff0000, v45
	v_lshlrev_b32_e32 v92, 16, v46
	v_and_b32_e32 v93, 0xffff0000, v46
	v_lshlrev_b32_e32 v94, 16, v47
	v_and_b32_e32 v95, 0xffff0000, v47
	v_pk_fma_f32 v[96:97], v[88:89], v[232:233], v[206:207]
	v_pk_fma_f32 v[98:99], v[90:91], v[234:235], v[208:209]
	v_pk_fma_f32 v[100:101], v[92:93], v[236:237], v[210:211]
	v_pk_fma_f32 v[102:103], v[94:95], v[238:239], v[212:213]
	v_lshlrev_b32_e32 v88, 16, v48
	v_and_b32_e32 v89, 0xffff0000, v48
	v_lshlrev_b32_e32 v90, 16, v49
	v_and_b32_e32 v91, 0xffff0000, v49
	v_lshlrev_b32_e32 v92, 16, v50
	v_and_b32_e32 v93, 0xffff0000, v50
	v_lshlrev_b32_e32 v94, 16, v51
	v_and_b32_e32 v95, 0xffff0000, v51
	v_pk_fma_f32 v[96:97], v[88:89], v[240:241], v[96:97]
	v_pk_fma_f32 v[98:99], v[90:91], v[242:243], v[98:99]
	v_pk_fma_f32 v[100:101], v[92:93], v[244:245], v[100:101]
	v_pk_fma_f32 v[102:103], v[94:95], v[246:247], v[102:103]
	v_pk_fma_f32 v[104:105], v[88:89], v[232:233], v[206:207]
	v_pk_fma_f32 v[106:107], v[90:91], v[234:235], v[208:209]
	v_pk_fma_f32 v[108:109], v[92:93], v[236:237], v[210:211]
	v_pk_fma_f32 v[110:111], v[94:95], v[238:239], v[212:213]
	v_lshlrev_b32_e32 v88, 16, v52
	v_and_b32_e32 v89, 0xffff0000, v52
	v_lshlrev_b32_e32 v90, 16, v53
	v_and_b32_e32 v91, 0xffff0000, v53
	v_lshlrev_b32_e32 v92, 16, v54
	v_and_b32_e32 v93, 0xffff0000, v54
	v_lshlrev_b32_e32 v94, 16, v55
	v_and_b32_e32 v95, 0xffff0000, v55
	v_pk_fma_f32 v[96:97], v[88:89], v[248:249], v[96:97]
	v_pk_fma_f32 v[98:99], v[90:91], v[250:251], v[98:99]
	v_pk_fma_f32 v[100:101], v[92:93], v[252:253], v[100:101]
	v_pk_fma_f32 v[102:103], v[94:95], v[254:255], v[102:103]
	v_pk_fma_f32 v[104:105], v[88:89], v[240:241], v[104:105]
	v_pk_fma_f32 v[106:107], v[90:91], v[242:243], v[106:107]
	v_pk_fma_f32 v[108:109], v[92:93], v[244:245], v[108:109]
	v_pk_fma_f32 v[110:111], v[94:95], v[246:247], v[110:111]
	v_pk_fma_f32 v[112:113], v[88:89], v[232:233], v[206:207]
	v_pk_fma_f32 v[114:115], v[90:91], v[234:235], v[208:209]
	v_pk_fma_f32 v[116:117], v[92:93], v[236:237], v[210:211]
	v_pk_fma_f32 v[118:119], v[94:95], v[238:239], v[212:213]
	v_lshlrev_b32_e32 v88, 16, v56
	v_and_b32_e32 v89, 0xffff0000, v56
	v_lshlrev_b32_e32 v90, 16, v57
	v_and_b32_e32 v91, 0xffff0000, v57
	v_lshlrev_b32_e32 v92, 16, v58
	v_and_b32_e32 v93, 0xffff0000, v58
	v_lshlrev_b32_e32 v94, 16, v59
	v_and_b32_e32 v95, 0xffff0000, v59
	v_pk_fma_f32 v[96:97], v[88:89], v[198:199], v[96:97]
	v_pk_fma_f32 v[98:99], v[90:91], v[200:201], v[98:99]
	v_pk_fma_f32 v[100:101], v[92:93], v[202:203], v[100:101]
	v_pk_fma_f32 v[102:103], v[94:95], v[204:205], v[102:103]
	v_pk_fma_f32 v[104:105], v[88:89], v[248:249], v[104:105]
; DI u32x4 pack8(const float (&f)[8]) { u32x4 w; w.x = pk2(f[0], f[1]); w.y = pk2(f[2], f[3]); w.z = pk2(f[4], f[5]); w.w = pk2(f[6], f[7]); return w; }
; DI void phase_conv(const Params& p) {
;     ...
;         for (int o = 0; o < 8; ++o) {
;             float acc[8];
; #pragma unroll
;             for (int e = 0; e < 8; ++e) acc[e] = bs[e];
; #pragma unroll
;             for (int jx = 0; jx < 4; ++jx) { float f[8]; unpack8(raw[o + jx], f);
; #pragma unroll
;                 for (int e = 0; e < 8; ++e) acc[e] += f[e] * wv[jx][e]; }
;             *(u32x4*)(xc + (size_t)(tok0 + o) * DM + ch) = pack8(acc);
	v_pk_fma_f32 v[106:107], v[90:91], v[250:251], v[106:107]
	v_pk_fma_f32 v[108:109], v[92:93], v[252:253], v[108:109]
	v_pk_fma_f32 v[110:111], v[94:95], v[254:255], v[110:111]
	v_pk_fma_f32 v[112:113], v[88:89], v[240:241], v[112:113]
	v_pk_fma_f32 v[114:115], v[90:91], v[242:243], v[114:115]
	v_pk_fma_f32 v[116:117], v[92:93], v[244:245], v[116:117]
	v_pk_fma_f32 v[118:119], v[94:95], v[246:247], v[118:119]
	v_pk_fma_f32 v[120:121], v[88:89], v[232:233], v[206:207]
	v_pk_fma_f32 v[122:123], v[90:91], v[234:235], v[208:209]
	v_pk_fma_f32 v[124:125], v[92:93], v[236:237], v[210:211]
	v_pk_fma_f32 v[126:127], v[94:95], v[238:239], v[212:213]
	v_cvt_pk_bf16_f32 v164, v96, v97
	v_cvt_pk_bf16_f32 v165, v98, v99
	v_cvt_pk_bf16_f32 v166, v100, v101
	v_cvt_pk_bf16_f32 v167, v102, v103
	global_store_dwordx4 v161, v[164:167], s[44:45] nt
	s_add_u32 s44, s44, 0x1000
	s_addc_u32 s45, s45, 0
	s_nop 1
	v_lshlrev_b32_e32 v88, 16, v60
	v_and_b32_e32 v89, 0xffff0000, v60
	v_lshlrev_b32_e32 v90, 16, v61
	v_and_b32_e32 v91, 0xffff0000, v61
	v_lshlrev_b32_e32 v92, 16, v62
	v_and_b32_e32 v93, 0xffff0000, v62
	v_lshlrev_b32_e32 v94, 16, v63
	v_and_b32_e32 v95, 0xffff0000, v63
	v_pk_fma_f32 v[104:105], v[88:89], v[198:199], v[104:105]
	v_pk_fma_f32 v[106:107], v[90:91], v[200:201], v[106:107]
	v_pk_fma_f32 v[108:109], v[92:93], v[202:203], v[108:109]
	v_pk_fma_f32 v[110:111], v[94:95], v[204:205], v[110:111]
	v_pk_fma_f32 v[112:113], v[88:89], v[248:249], v[112:113]
	v_pk_fma_f32 v[114:115], v[90:91], v[250:251], v[114:115]
	v_pk_fma_f32 v[116:117], v[92:93], v[252:253], v[116:117]
	v_pk_fma_f32 v[118:119], v[94:95], v[254:255], v[118:119]
	v_pk_fma_f32 v[120:121], v[88:89], v[240:241], v[120:121]
	v_pk_fma_f32 v[122:123], v[90:91], v[242:243], v[122:123]
	v_pk_fma_f32 v[124:125], v[92:93], v[244:245], v[124:125]
	v_pk_fma_f32 v[126:127], v[94:95], v[246:247], v[126:127]
	v_pk_fma_f32 v[128:129], v[88:89], v[232:233], v[206:207]
	v_pk_fma_f32 v[130:131], v[90:91], v[234:235], v[208:209]
	v_pk_fma_f32 v[132:133], v[92:93], v[236:237], v[210:211]
	v_pk_fma_f32 v[134:135], v[94:95], v[238:239], v[212:213]
	v_cvt_pk_bf16_f32 v164, v104, v105
	v_cvt_pk_bf16_f32 v165, v106, v107
	v_cvt_pk_bf16_f32 v166, v108, v109
	v_cvt_pk_bf16_f32 v167, v110, v111
	global_store_dwordx4 v161, v[164:167], s[44:45] nt
	s_add_u32 s44, s44, 0x1000
	s_addc_u32 s45, s45, 0
	s_nop 1
	v_lshlrev_b32_e32 v88, 16, v64
	v_and_b32_e32 v89, 0xffff0000, v64
	v_lshlrev_b32_e32 v90, 16, v65
	v_and_b32_e32 v91, 0xffff0000, v65
	v_lshlrev_b32_e32 v92, 16, v66
	v_and_b32_e32 v93, 0xffff0000, v66
	v_lshlrev_b32_e32 v94, 16, v67
	v_and_b32_e32 v95, 0xffff0000, v67
	v_pk_fma_f32 v[112:113], v[88:89], v[198:199], v[112:113]
	v_pk_fma_f32 v[114:115], v[90:91], v[200:201], v[114:115]
	v_pk_fma_f32 v[116:117], v[92:93], v[202:203], v[116:117]
	v_pk_fma_f32 v[118:119], v[94:95], v[204:205], v[118:119]
	v_pk_fma_f32 v[120:121], v[88:89], v[248:249], v[120:121]
	v_pk_fma_f32 v[122:123], v[90:91], v[250:251], v[122:123]
	v_pk_fma_f32 v[124:125], v[92:93], v[252:253], v[124:125]
	v_pk_fma_f32 v[126:127], v[94:95], v[254:255], v[126:127]
	v_pk_fma_f32 v[128:129], v[88:89], v[240:241], v[128:129]
	v_pk_fma_f32 v[130:131], v[90:91], v[242:243], v[130:131]
	v_pk_fma_f32 v[132:133], v[92:93], v[244:245], v[132:133]
	v_pk_fma_f32 v[134:135], v[94:95], v[246:247], v[134:135]
	v_pk_fma_f32 v[136:137], v[88:89], v[232:233], v[206:207]
	v_pk_fma_f32 v[138:139], v[90:91], v[234:235], v[208:209]
	v_pk_fma_f32 v[140:141], v[92:93], v[236:237], v[210:211]
	v_pk_fma_f32 v[142:143], v[94:95], v[238:239], v[212:213]
	v_cvt_pk_bf16_f32 v164, v112, v113
	v_cvt_pk_bf16_f32 v165, v114, v115
	v_cvt_pk_bf16_f32 v166, v116, v117
	v_cvt_pk_bf16_f32 v167, v118, v119
	global_store_dwordx4 v161, v[164:167], s[44:45] nt
	s_add_u32 s44, s44, 0x1000
	s_addc_u32 s45, s45, 0
	s_nop 1
	v_lshlrev_b32_e32 v88, 16, v68
	v_and_b32_e32 v89, 0xffff0000, v68
	v_lshlrev_b32_e32 v90, 16, v69
	v_and_b32_e32 v91, 0xffff0000, v69
	v_lshlrev_b32_e32 v92, 16, v70
	v_and_b32_e32 v93, 0xffff0000, v70
	v_lshlrev_b32_e32 v94, 16, v71
	v_and_b32_e32 v95, 0xffff0000, v71
	v_pk_fma_f32 v[120:121], v[88:89], v[198:199], v[120:121]
	v_pk_fma_f32 v[122:123], v[90:91], v[200:201], v[122:123]
	v_pk_fma_f32 v[124:125], v[92:93], v[202:203], v[124:125]
	v_pk_fma_f32 v[126:127], v[94:95], v[204:205], v[126:127]
	v_pk_fma_f32 v[128:129], v[88:89], v[248:249], v[128:129]
	v_pk_fma_f32 v[130:131], v[90:91], v[250:251], v[130:131]
	v_pk_fma_f32 v[132:133], v[92:93], v[252:253], v[132:133]
	v_pk_fma_f32 v[134:135], v[94:95], v[254:255], v[134:135]
	v_pk_fma_f32 v[136:137], v[88:89], v[240:241], v[136:137]
	v_pk_fma_f32 v[138:139], v[90:91], v[242:243], v[138:139]
	v_pk_fma_f32 v[140:141], v[92:93], v[244:245], v[140:141]
	v_pk_fma_f32 v[142:143], v[94:95], v[246:247], v[142:143]
	v_pk_fma_f32 v[144:145], v[88:89], v[232:233], v[206:207]
	v_pk_fma_f32 v[146:147], v[90:91], v[234:235], v[208:209]
	v_pk_fma_f32 v[148:149], v[92:93], v[236:237], v[210:211]
	v_pk_fma_f32 v[150:151], v[94:95], v[238:239], v[212:213]
	v_cvt_pk_bf16_f32 v164, v120, v121
	v_cvt_pk_bf16_f32 v165, v122, v123
	v_cvt_pk_bf16_f32 v166, v124, v125
	v_cvt_pk_bf16_f32 v167, v126, v127
	global_store_dwordx4 v161, v[164:167], s[44:45] nt
	s_add_u32 s44, s44, 0x1000
	s_addc_u32 s45, s45, 0
	s_nop 1
	v_lshlrev_b32_e32 v88, 16, v72
	v_and_b32_e32 v89, 0xffff0000, v72
	v_lshlrev_b32_e32 v90, 16, v73
	v_and_b32_e32 v91, 0xffff0000, v73
	v_lshlrev_b32_e32 v92, 16, v74
	v_and_b32_e32 v93, 0xffff0000, v74
	v_lshlrev_b32_e32 v94, 16, v75
	v_and_b32_e32 v95, 0xffff0000, v75
	v_pk_fma_f32 v[128:129], v[88:89], v[198:199], v[128:129]
; DI u32x4 pack8(const float (&f)[8]) { u32x4 w; w.x = pk2(f[0], f[1]); w.y = pk2(f[2], f[3]); w.z = pk2(f[4], f[5]); w.w = pk2(f[6], f[7]); return w; }
; DI void phase_conv(const Params& p) {
;     ...
;         for (int r = 0; r < 11; ++r) raw[r] = (r >= 3 || t0 > 0) ? *(const u32x4*)(big + (size_t)(tok0 - 3 + r) * 4096 + ch) : (u32x4){0u, 0u, 0u, 0u};
; #pragma unroll
;         for (int o = 0; o < 8; ++o) {
;             float acc[8];
; #pragma unroll
;             for (int e = 0; e < 8; ++e) acc[e] = bs[e];
; #pragma unroll
;             for (int jx = 0; jx < 4; ++jx) { float f[8]; unpack8(raw[o + jx], f);
; #pragma unroll
;                 for (int e = 0; e < 8; ++e) acc[e] += f[e] * wv[jx][e]; }
;             *(u32x4*)(xc + (size_t)(tok0 + o) * DM + ch) = pack8(acc);
	v_pk_fma_f32 v[130:131], v[90:91], v[200:201], v[130:131]
	v_pk_fma_f32 v[132:133], v[92:93], v[202:203], v[132:133]
	v_pk_fma_f32 v[134:135], v[94:95], v[204:205], v[134:135]
	v_pk_fma_f32 v[136:137], v[88:89], v[248:249], v[136:137]
	v_pk_fma_f32 v[138:139], v[90:91], v[250:251], v[138:139]
	v_pk_fma_f32 v[140:141], v[92:93], v[252:253], v[140:141]
	v_pk_fma_f32 v[142:143], v[94:95], v[254:255], v[142:143]
	v_pk_fma_f32 v[144:145], v[88:89], v[240:241], v[144:145]
	v_pk_fma_f32 v[146:147], v[90:91], v[242:243], v[146:147]
	v_pk_fma_f32 v[148:149], v[92:93], v[244:245], v[148:149]
	v_pk_fma_f32 v[150:151], v[94:95], v[246:247], v[150:151]
	v_pk_fma_f32 v[152:153], v[88:89], v[232:233], v[206:207]
	v_pk_fma_f32 v[154:155], v[90:91], v[234:235], v[208:209]
	v_pk_fma_f32 v[156:157], v[92:93], v[236:237], v[210:211]
	v_pk_fma_f32 v[158:159], v[94:95], v[238:239], v[212:213]
	v_cvt_pk_bf16_f32 v164, v128, v129
	v_cvt_pk_bf16_f32 v165, v130, v131
	v_cvt_pk_bf16_f32 v166, v132, v133
	v_cvt_pk_bf16_f32 v167, v134, v135
	global_store_dwordx4 v161, v[164:167], s[44:45] nt
	s_add_u32 s44, s44, 0x1000
	s_addc_u32 s45, s45, 0
	s_nop 1
	v_lshlrev_b32_e32 v88, 16, v76
	v_and_b32_e32 v89, 0xffff0000, v76
	v_lshlrev_b32_e32 v90, 16, v77
	v_and_b32_e32 v91, 0xffff0000, v77
	v_lshlrev_b32_e32 v92, 16, v78
	v_and_b32_e32 v93, 0xffff0000, v78
	v_lshlrev_b32_e32 v94, 16, v79
	v_and_b32_e32 v95, 0xffff0000, v79
	v_pk_fma_f32 v[136:137], v[88:89], v[198:199], v[136:137]
	v_pk_fma_f32 v[138:139], v[90:91], v[200:201], v[138:139]
	v_pk_fma_f32 v[140:141], v[92:93], v[202:203], v[140:141]
	v_pk_fma_f32 v[142:143], v[94:95], v[204:205], v[142:143]
	v_pk_fma_f32 v[144:145], v[88:89], v[248:249], v[144:145]
	v_pk_fma_f32 v[146:147], v[90:91], v[250:251], v[146:147]
	v_pk_fma_f32 v[148:149], v[92:93], v[252:253], v[148:149]
	v_pk_fma_f32 v[150:151], v[94:95], v[254:255], v[150:151]
	v_pk_fma_f32 v[152:153], v[88:89], v[240:241], v[152:153]
	v_pk_fma_f32 v[154:155], v[90:91], v[242:243], v[154:155]
	v_pk_fma_f32 v[156:157], v[92:93], v[244:245], v[156:157]
	v_pk_fma_f32 v[158:159], v[94:95], v[246:247], v[158:159]
	v_cvt_pk_bf16_f32 v164, v136, v137
	v_cvt_pk_bf16_f32 v165, v138, v139
	v_cvt_pk_bf16_f32 v166, v140, v141
	v_cvt_pk_bf16_f32 v167, v142, v143
	global_store_dwordx4 v161, v[164:167], s[44:45] nt
	s_add_u32 s44, s44, 0x1000
	s_addc_u32 s45, s45, 0
	s_nop 1
	v_lshlrev_b32_e32 v88, 16, v80
	v_and_b32_e32 v89, 0xffff0000, v80
	v_lshlrev_b32_e32 v90, 16, v81
	v_and_b32_e32 v91, 0xffff0000, v81
	v_lshlrev_b32_e32 v92, 16, v82
	v_and_b32_e32 v93, 0xffff0000, v82
	v_lshlrev_b32_e32 v94, 16, v83
	v_and_b32_e32 v95, 0xffff0000, v83
	v_pk_fma_f32 v[144:145], v[88:89], v[198:199], v[144:145]
	v_pk_fma_f32 v[146:147], v[90:91], v[200:201], v[146:147]
	v_pk_fma_f32 v[148:149], v[92:93], v[202:203], v[148:149]
	v_pk_fma_f32 v[150:151], v[94:95], v[204:205], v[150:151]
	v_pk_fma_f32 v[152:153], v[88:89], v[248:249], v[152:153]
	v_pk_fma_f32 v[154:155], v[90:91], v[250:251], v[154:155]
	v_pk_fma_f32 v[156:157], v[92:93], v[252:253], v[156:157]
	v_pk_fma_f32 v[158:159], v[94:95], v[254:255], v[158:159]
	v_cvt_pk_bf16_f32 v164, v144, v145
	v_cvt_pk_bf16_f32 v165, v146, v147
	v_cvt_pk_bf16_f32 v166, v148, v149
	v_cvt_pk_bf16_f32 v167, v150, v151
	global_store_dwordx4 v161, v[164:167], s[44:45] nt
	s_add_u32 s44, s44, 0x1000
	s_addc_u32 s45, s45, 0
	s_nop 1
	v_lshlrev_b32_e32 v88, 16, v84
	v_and_b32_e32 v89, 0xffff0000, v84
	v_lshlrev_b32_e32 v90, 16, v85
	v_and_b32_e32 v91, 0xffff0000, v85
	v_lshlrev_b32_e32 v92, 16, v86
	v_and_b32_e32 v93, 0xffff0000, v86
	v_lshlrev_b32_e32 v94, 16, v87
	v_and_b32_e32 v95, 0xffff0000, v87
	v_pk_fma_f32 v[152:153], v[88:89], v[198:199], v[152:153]
	v_pk_fma_f32 v[154:155], v[90:91], v[200:201], v[154:155]
	v_pk_fma_f32 v[156:157], v[92:93], v[202:203], v[156:157]
	v_pk_fma_f32 v[158:159], v[94:95], v[204:205], v[158:159]
	v_cvt_pk_bf16_f32 v164, v152, v153
	v_cvt_pk_bf16_f32 v165, v154, v155
	v_cvt_pk_bf16_f32 v166, v156, v157
	v_cvt_pk_bf16_f32 v167, v158, v159
	global_store_dwordx4 v161, v[164:167], s[44:45] nt
	s_add_u32 s44, s44, 0x1000
	s_addc_u32 s45, s45, 0
	s_nop 1
	s_add_u32 s28, s28, 0x1000000
	s_addc_u32 s29, s29, 0
	s_mov_b64 s[44:45], s[26:27]
	global_load_dwordx4 v[44:47], v160, s[44:45]
	s_add_u32 s44, s44, 0x2000
	s_addc_u32 s45, s45, 0
	global_load_dwordx4 v[48:51], v160, s[44:45]
	s_add_u32 s44, s44, 0x2000
	s_addc_u32 s45, s45, 0
	global_load_dwordx4 v[52:55], v160, s[44:45]
	s_add_u32 s44, s44, 0x2000
	s_addc_u32 s45, s45, 0
	global_load_dwordx4 v[56:59], v160, s[44:45]
	s_add_u32 s44, s44, 0x2000
	s_addc_u32 s45, s45, 0
	global_load_dwordx4 v[60:63], v160, s[44:45]
	s_add_u32 s44, s44, 0x2000
	s_addc_u32 s45, s45, 0
	global_load_dwordx4 v[64:67], v160, s[44:45]
	s_add_u32 s44, s44, 0x2000
	s_addc_u32 s45, s45, 0
	global_load_dwordx4 v[68:71], v160, s[44:45]
	s_add_u32 s44, s44, 0x2000
	s_addc_u32 s45, s45, 0
	global_load_dwordx4 v[72:75], v160, s[44:45]
	s_add_u32 s44, s44, 0x2000
	s_addc_u32 s45, s45, 0
	global_load_dwordx4 v[76:79], v160, s[44:45]
	s_add_u32 s44, s44, 0x2000
	s_addc_u32 s45, s45, 0
	global_load_dwordx4 v[80:83], v160, s[44:45]
	s_add_u32 s44, s44, 0x2000
	s_addc_u32 s45, s45, 0
	global_load_dwordx4 v[84:87], v160, s[44:45]
	s_add_u32 s26, s26, 0x2000000
	s_addc_u32 s27, s27, 0
	s_waitcnt vmcnt(19)
	s_cmp_eq_u32 s40, 0
	s_cbranch_scc0 .Lcv_nopad2
	v_mov_b32_e32 v0, 0
	v_mov_b32_e32 v1, 0
	v_mov_b32_e32 v2, 0
	v_mov_b32_e32 v3, 0
	v_mov_b32_e32 v4, 0
	v_mov_b32_e32 v5, 0
	v_mov_b32_e32 v6, 0
	v_mov_b32_e32 v7, 0
	v_mov_b32_e32 v8, 0
	v_mov_b32_e32 v9, 0
	v_mov_b32_e32 v10, 0
	v_mov_b32_e32 v11, 0
; DI u32x4 pack8(const float (&f)[8]) { u32x4 w; w.x = pk2(f[0], f[1]); w.y = pk2(f[2], f[3]); w.z = pk2(f[4], f[5]); w.w = pk2(f[6], f[7]); return w; }
; DI void phase_conv(const Params& p) {
;     ...
;         for (int o = 0; o < 8; ++o) {
;             float acc[8];
; #pragma unroll
;             for (int e = 0; e < 8; ++e) acc[e] = bs[e];
; #pragma unroll
;             for (int jx = 0; jx < 4; ++jx) { float f[8]; unpack8(raw[o + jx], f);
; #pragma unroll
;                 for (int e = 0; e < 8; ++e) acc[e] += f[e] * wv[jx][e]; }
;             *(u32x4*)(xc + (size_t)(tok0 + o) * DM + ch) = pack8(acc);
.Lcv_nopad2:
	s_mov_b64 s[44:45], s[28:29]
	v_lshlrev_b32_e32 v88, 16, v0
	v_and_b32_e32 v89, 0xffff0000, v0
	v_lshlrev_b32_e32 v90, 16, v1
	v_and_b32_e32 v91, 0xffff0000, v1
	v_lshlrev_b32_e32 v92, 16, v2
	v_and_b32_e32 v93, 0xffff0000, v2
	v_lshlrev_b32_e32 v94, 16, v3
	v_and_b32_e32 v95, 0xffff0000, v3
	v_pk_fma_f32 v[96:97], v[88:89], v[232:233], v[206:207]
	v_pk_fma_f32 v[98:99], v[90:91], v[234:235], v[208:209]
	v_pk_fma_f32 v[100:101], v[92:93], v[236:237], v[210:211]
	v_pk_fma_f32 v[102:103], v[94:95], v[238:239], v[212:213]
	v_lshlrev_b32_e32 v88, 16, v4
	v_and_b32_e32 v89, 0xffff0000, v4
	v_lshlrev_b32_e32 v90, 16, v5
	v_and_b32_e32 v91, 0xffff0000, v5
	v_lshlrev_b32_e32 v92, 16, v6
	v_and_b32_e32 v93, 0xffff0000, v6
	v_lshlrev_b32_e32 v94, 16, v7
	v_and_b32_e32 v95, 0xffff0000, v7
	v_pk_fma_f32 v[96:97], v[88:89], v[240:241], v[96:97]
	v_pk_fma_f32 v[98:99], v[90:91], v[242:243], v[98:99]
	v_pk_fma_f32 v[100:101], v[92:93], v[244:245], v[100:101]
	v_pk_fma_f32 v[102:103], v[94:95], v[246:247], v[102:103]
	v_pk_fma_f32 v[104:105], v[88:89], v[232:233], v[206:207]
	v_pk_fma_f32 v[106:107], v[90:91], v[234:235], v[208:209]
	v_pk_fma_f32 v[108:109], v[92:93], v[236:237], v[210:211]
	v_pk_fma_f32 v[110:111], v[94:95], v[238:239], v[212:213]
	v_lshlrev_b32_e32 v88, 16, v8
	v_and_b32_e32 v89, 0xffff0000, v8
	v_lshlrev_b32_e32 v90, 16, v9
	v_and_b32_e32 v91, 0xffff0000, v9
	v_lshlrev_b32_e32 v92, 16, v10
	v_and_b32_e32 v93, 0xffff0000, v10
	v_lshlrev_b32_e32 v94, 16, v11
	v_and_b32_e32 v95, 0xffff0000, v11
	v_pk_fma_f32 v[96:97], v[88:89], v[248:249], v[96:97]
	v_pk_fma_f32 v[98:99], v[90:91], v[250:251], v[98:99]
	v_pk_fma_f32 v[100:101], v[92:93], v[252:253], v[100:101]
	v_pk_fma_f32 v[102:103], v[94:95], v[254:255], v[102:103]
	v_pk_fma_f32 v[104:105], v[88:89], v[240:241], v[104:105]
	v_pk_fma_f32 v[106:107], v[90:91], v[242:243], v[106:107]
	v_pk_fma_f32 v[108:109], v[92:93], v[244:245], v[108:109]
	v_pk_fma_f32 v[110:111], v[94:95], v[246:247], v[110:111]
	v_pk_fma_f32 v[112:113], v[88:89], v[232:233], v[206:207]
	v_pk_fma_f32 v[114:115], v[90:91], v[234:235], v[208:209]
	v_pk_fma_f32 v[116:117], v[92:93], v[236:237], v[210:211]
	v_pk_fma_f32 v[118:119], v[94:95], v[238:239], v[212:213]
	v_lshlrev_b32_e32 v88, 16, v12
	v_and_b32_e32 v89, 0xffff0000, v12
	v_lshlrev_b32_e32 v90, 16, v13
	v_and_b32_e32 v91, 0xffff0000, v13
	v_lshlrev_b32_e32 v92, 16, v14
	v_and_b32_e32 v93, 0xffff0000, v14
	v_lshlrev_b32_e32 v94, 16, v15
	v_and_b32_e32 v95, 0xffff0000, v15
	v_pk_fma_f32 v[96:97], v[88:89], v[198:199], v[96:97]
	v_pk_fma_f32 v[98:99], v[90:91], v[200:201], v[98:99]
	v_pk_fma_f32 v[100:101], v[92:93], v[202:203], v[100:101]
	v_pk_fma_f32 v[102:103], v[94:95], v[204:205], v[102:103]
	v_pk_fma_f32 v[104:105], v[88:89], v[248:249], v[104:105]
	v_pk_fma_f32 v[106:107], v[90:91], v[250:251], v[106:107]
	v_pk_fma_f32 v[108:109], v[92:93], v[252:253], v[108:109]
	v_pk_fma_f32 v[110:111], v[94:95], v[254:255], v[110:111]
	v_pk_fma_f32 v[112:113], v[88:89], v[240:241], v[112:113]
	v_pk_fma_f32 v[114:115], v[90:91], v[242:243], v[114:115]
	v_pk_fma_f32 v[116:117], v[92:93], v[244:245], v[116:117]
	v_pk_fma_f32 v[118:119], v[94:95], v[246:247], v[118:119]
	v_pk_fma_f32 v[120:121], v[88:89], v[232:233], v[206:207]
	v_pk_fma_f32 v[122:123], v[90:91], v[234:235], v[208:209]
	v_pk_fma_f32 v[124:125], v[92:93], v[236:237], v[210:211]
	v_pk_fma_f32 v[126:127], v[94:95], v[238:239], v[212:213]
	v_cvt_pk_bf16_f32 v164, v96, v97
	v_cvt_pk_bf16_f32 v165, v98, v99
	v_cvt_pk_bf16_f32 v166, v100, v101
	v_cvt_pk_bf16_f32 v167, v102, v103
	global_store_dwordx4 v161, v[164:167], s[44:45] nt
	s_add_u32 s44, s44, 0x1000
	s_addc_u32 s45, s45, 0
	s_nop 1
	v_lshlrev_b32_e32 v88, 16, v16
	v_and_b32_e32 v89, 0xffff0000, v16
	v_lshlrev_b32_e32 v90, 16, v17
	v_and_b32_e32 v91, 0xffff0000, v17
	v_lshlrev_b32_e32 v92, 16, v18
	v_and_b32_e32 v93, 0xffff0000, v18
	v_lshlrev_b32_e32 v94, 16, v19
	v_and_b32_e32 v95, 0xffff0000, v19
	v_pk_fma_f32 v[104:105], v[88:89], v[198:199], v[104:105]
	v_pk_fma_f32 v[106:107], v[90:91], v[200:201], v[106:107]
	v_pk_fma_f32 v[108:109], v[92:93], v[202:203], v[108:109]
	v_pk_fma_f32 v[110:111], v[94:95], v[204:205], v[110:111]
	v_pk_fma_f32 v[112:113], v[88:89], v[248:249], v[112:113]
	v_pk_fma_f32 v[114:115], v[90:91], v[250:251], v[114:115]
	v_pk_fma_f32 v[116:117], v[92:93], v[252:253], v[116:117]
	v_pk_fma_f32 v[118:119], v[94:95], v[254:255], v[118:119]
	v_pk_fma_f32 v[120:121], v[88:89], v[240:241], v[120:121]
	v_pk_fma_f32 v[122:123], v[90:91], v[242:243], v[122:123]
	v_pk_fma_f32 v[124:125], v[92:93], v[244:245], v[124:125]
	v_pk_fma_f32 v[126:127], v[94:95], v[246:247], v[126:127]
	v_pk_fma_f32 v[128:129], v[88:89], v[232:233], v[206:207]
	v_pk_fma_f32 v[130:131], v[90:91], v[234:235], v[208:209]
	v_pk_fma_f32 v[132:133], v[92:93], v[236:237], v[210:211]
	v_pk_fma_f32 v[134:135], v[94:95], v[238:239], v[212:213]
	v_cvt_pk_bf16_f32 v164, v104, v105
	v_cvt_pk_bf16_f32 v165, v106, v107
	v_cvt_pk_bf16_f32 v166, v108, v109
	v_cvt_pk_bf16_f32 v167, v110, v111
	global_store_dwordx4 v161, v[164:167], s[44:45] nt
	s_add_u32 s44, s44, 0x1000
	s_addc_u32 s45, s45, 0
	s_nop 1
	v_lshlrev_b32_e32 v88, 16, v20
	v_and_b32_e32 v89, 0xffff0000, v20
	v_lshlrev_b32_e32 v90, 16, v21
	v_and_b32_e32 v91, 0xffff0000, v21
	v_lshlrev_b32_e32 v92, 16, v22
	v_and_b32_e32 v93, 0xffff0000, v22
	v_lshlrev_b32_e32 v94, 16, v23
	v_and_b32_e32 v95, 0xffff0000, v23
	v_pk_fma_f32 v[112:113], v[88:89], v[198:199], v[112:113]
	v_pk_fma_f32 v[114:115], v[90:91], v[200:201], v[114:115]
	v_pk_fma_f32 v[116:117], v[92:93], v[202:203], v[116:117]
; DI u32x4 pack8(const float (&f)[8]) { u32x4 w; w.x = pk2(f[0], f[1]); w.y = pk2(f[2], f[3]); w.z = pk2(f[4], f[5]); w.w = pk2(f[6], f[7]); return w; }
; DI void phase_conv(const Params& p) {
;     ...
;         for (int o = 0; o < 8; ++o) {
;             float acc[8];
; #pragma unroll
;             for (int e = 0; e < 8; ++e) acc[e] = bs[e];
; #pragma unroll
;             for (int jx = 0; jx < 4; ++jx) { float f[8]; unpack8(raw[o + jx], f);
; #pragma unroll
;                 for (int e = 0; e < 8; ++e) acc[e] += f[e] * wv[jx][e]; }
;             *(u32x4*)(xc + (size_t)(tok0 + o) * DM + ch) = pack8(acc);
	v_pk_fma_f32 v[118:119], v[94:95], v[204:205], v[118:119]
	v_pk_fma_f32 v[120:121], v[88:89], v[248:249], v[120:121]
	v_pk_fma_f32 v[122:123], v[90:91], v[250:251], v[122:123]
	v_pk_fma_f32 v[124:125], v[92:93], v[252:253], v[124:125]
	v_pk_fma_f32 v[126:127], v[94:95], v[254:255], v[126:127]
	v_pk_fma_f32 v[128:129], v[88:89], v[240:241], v[128:129]
	v_pk_fma_f32 v[130:131], v[90:91], v[242:243], v[130:131]
	v_pk_fma_f32 v[132:133], v[92:93], v[244:245], v[132:133]
	v_pk_fma_f32 v[134:135], v[94:95], v[246:247], v[134:135]
	v_pk_fma_f32 v[136:137], v[88:89], v[232:233], v[206:207]
	v_pk_fma_f32 v[138:139], v[90:91], v[234:235], v[208:209]
	v_pk_fma_f32 v[140:141], v[92:93], v[236:237], v[210:211]
	v_pk_fma_f32 v[142:143], v[94:95], v[238:239], v[212:213]
	v_cvt_pk_bf16_f32 v164, v112, v113
	v_cvt_pk_bf16_f32 v165, v114, v115
	v_cvt_pk_bf16_f32 v166, v116, v117
	v_cvt_pk_bf16_f32 v167, v118, v119
	global_store_dwordx4 v161, v[164:167], s[44:45] nt
	s_add_u32 s44, s44, 0x1000
	s_addc_u32 s45, s45, 0
	s_nop 1
	v_lshlrev_b32_e32 v88, 16, v24
	v_and_b32_e32 v89, 0xffff0000, v24
	v_lshlrev_b32_e32 v90, 16, v25
	v_and_b32_e32 v91, 0xffff0000, v25
	v_lshlrev_b32_e32 v92, 16, v26
	v_and_b32_e32 v93, 0xffff0000, v26
	v_lshlrev_b32_e32 v94, 16, v27
	v_and_b32_e32 v95, 0xffff0000, v27
	v_pk_fma_f32 v[120:121], v[88:89], v[198:199], v[120:121]
	v_pk_fma_f32 v[122:123], v[90:91], v[200:201], v[122:123]
	v_pk_fma_f32 v[124:125], v[92:93], v[202:203], v[124:125]
	v_pk_fma_f32 v[126:127], v[94:95], v[204:205], v[126:127]
	v_pk_fma_f32 v[128:129], v[88:89], v[248:249], v[128:129]
	v_pk_fma_f32 v[130:131], v[90:91], v[250:251], v[130:131]
	v_pk_fma_f32 v[132:133], v[92:93], v[252:253], v[132:133]
	v_pk_fma_f32 v[134:135], v[94:95], v[254:255], v[134:135]
	v_pk_fma_f32 v[136:137], v[88:89], v[240:241], v[136:137]
	v_pk_fma_f32 v[138:139], v[90:91], v[242:243], v[138:139]
	v_pk_fma_f32 v[140:141], v[92:93], v[244:245], v[140:141]
	v_pk_fma_f32 v[142:143], v[94:95], v[246:247], v[142:143]
	v_pk_fma_f32 v[144:145], v[88:89], v[232:233], v[206:207]
	v_pk_fma_f32 v[146:147], v[90:91], v[234:235], v[208:209]
	v_pk_fma_f32 v[148:149], v[92:93], v[236:237], v[210:211]
	v_pk_fma_f32 v[150:151], v[94:95], v[238:239], v[212:213]
	v_cvt_pk_bf16_f32 v164, v120, v121
	v_cvt_pk_bf16_f32 v165, v122, v123
	v_cvt_pk_bf16_f32 v166, v124, v125
	v_cvt_pk_bf16_f32 v167, v126, v127
	global_store_dwordx4 v161, v[164:167], s[44:45] nt
	s_add_u32 s44, s44, 0x1000
	s_addc_u32 s45, s45, 0
	s_nop 1
	v_lshlrev_b32_e32 v88, 16, v28
	v_and_b32_e32 v89, 0xffff0000, v28
	v_lshlrev_b32_e32 v90, 16, v29
	v_and_b32_e32 v91, 0xffff0000, v29
	v_lshlrev_b32_e32 v92, 16, v30
	v_and_b32_e32 v93, 0xffff0000, v30
	v_lshlrev_b32_e32 v94, 16, v31
	v_and_b32_e32 v95, 0xffff0000, v31
	v_pk_fma_f32 v[128:129], v[88:89], v[198:199], v[128:129]
	v_pk_fma_f32 v[130:131], v[90:91], v[200:201], v[130:131]
	v_pk_fma_f32 v[132:133], v[92:93], v[202:203], v[132:133]
	v_pk_fma_f32 v[134:135], v[94:95], v[204:205], v[134:135]
	v_pk_fma_f32 v[136:137], v[88:89], v[248:249], v[136:137]
	v_pk_fma_f32 v[138:139], v[90:91], v[250:251], v[138:139]
	v_pk_fma_f32 v[140:141], v[92:93], v[252:253], v[140:141]
	v_pk_fma_f32 v[142:143], v[94:95], v[254:255], v[142:143]
	v_pk_fma_f32 v[144:145], v[88:89], v[240:241], v[144:145]
	v_pk_fma_f32 v[146:147], v[90:91], v[242:243], v[146:147]
	v_pk_fma_f32 v[148:149], v[92:93], v[244:245], v[148:149]
	v_pk_fma_f32 v[150:151], v[94:95], v[246:247], v[150:151]
	v_pk_fma_f32 v[152:153], v[88:89], v[232:233], v[206:207]
	v_pk_fma_f32 v[154:155], v[90:91], v[234:235], v[208:209]
	v_pk_fma_f32 v[156:157], v[92:93], v[236:237], v[210:211]
	v_pk_fma_f32 v[158:159], v[94:95], v[238:239], v[212:213]
	v_cvt_pk_bf16_f32 v164, v128, v129
	v_cvt_pk_bf16_f32 v165, v130, v131
	v_cvt_pk_bf16_f32 v166, v132, v133
	v_cvt_pk_bf16_f32 v167, v134, v135
	global_store_dwordx4 v161, v[164:167], s[44:45] nt
	s_add_u32 s44, s44, 0x1000
	s_addc_u32 s45, s45, 0
	s_nop 1
	v_lshlrev_b32_e32 v88, 16, v32
	v_and_b32_e32 v89, 0xffff0000, v32
	v_lshlrev_b32_e32 v90, 16, v33
	v_and_b32_e32 v91, 0xffff0000, v33
	v_lshlrev_b32_e32 v92, 16, v34
	v_and_b32_e32 v93, 0xffff0000, v34
	v_lshlrev_b32_e32 v94, 16, v35
	v_and_b32_e32 v95, 0xffff0000, v35
	v_pk_fma_f32 v[136:137], v[88:89], v[198:199], v[136:137]
	v_pk_fma_f32 v[138:139], v[90:91], v[200:201], v[138:139]
	v_pk_fma_f32 v[140:141], v[92:93], v[202:203], v[140:141]
	v_pk_fma_f32 v[142:143], v[94:95], v[204:205], v[142:143]
	v_pk_fma_f32 v[144:145], v[88:89], v[248:249], v[144:145]
	v_pk_fma_f32 v[146:147], v[90:91], v[250:251], v[146:147]
	v_pk_fma_f32 v[148:149], v[92:93], v[252:253], v[148:149]
	v_pk_fma_f32 v[150:151], v[94:95], v[254:255], v[150:151]
	v_pk_fma_f32 v[152:153], v[88:89], v[240:241], v[152:153]
	v_pk_fma_f32 v[154:155], v[90:91], v[242:243], v[154:155]
	v_pk_fma_f32 v[156:157], v[92:93], v[244:245], v[156:157]
	v_pk_fma_f32 v[158:159], v[94:95], v[246:247], v[158:159]
	v_cvt_pk_bf16_f32 v164, v136, v137
	v_cvt_pk_bf16_f32 v165, v138, v139
	v_cvt_pk_bf16_f32 v166, v140, v141
	v_cvt_pk_bf16_f32 v167, v142, v143
	global_store_dwordx4 v161, v[164:167], s[44:45] nt
	s_add_u32 s44, s44, 0x1000
	s_addc_u32 s45, s45, 0
	s_nop 1
	v_lshlrev_b32_e32 v88, 16, v36
	v_and_b32_e32 v89, 0xffff0000, v36
	v_lshlrev_b32_e32 v90, 16, v37
	v_and_b32_e32 v91, 0xffff0000, v37
	v_lshlrev_b32_e32 v92, 16, v38
	v_and_b32_e32 v93, 0xffff0000, v38
	v_lshlrev_b32_e32 v94, 16, v39
	v_and_b32_e32 v95, 0xffff0000, v39
	v_pk_fma_f32 v[144:145], v[88:89], v[198:199], v[144:145]
	v_pk_fma_f32 v[146:147], v[90:91], v[200:201], v[146:147]
	v_pk_fma_f32 v[148:149], v[92:93], v[202:203], v[148:149]
	v_pk_fma_f32 v[150:151], v[94:95], v[204:205], v[150:151]
	v_pk_fma_f32 v[152:153], v[88:89], v[248:249], v[152:153]
	v_pk_fma_f32 v[154:155], v[90:91], v[250:251], v[154:155]
	v_pk_fma_f32 v[156:157], v[92:93], v[252:253], v[156:157]
	v_pk_fma_f32 v[158:159], v[94:95], v[254:255], v[158:159]
	v_cvt_pk_bf16_f32 v164, v144, v145
	v_cvt_pk_bf16_f32 v165, v146, v147
	v_cvt_pk_bf16_f32 v166, v148, v149
	v_cvt_pk_bf16_f32 v167, v150, v151
	global_store_dwordx4 v161, v[164:167], s[44:45] nt
	s_add_u32 s44, s44, 0x1000
	s_addc_u32 s45, s45, 0
	s_nop 1
	v_lshlrev_b32_e32 v88, 16, v40
	v_and_b32_e32 v89, 0xffff0000, v40
	v_lshlrev_b32_e32 v90, 16, v41
	v_and_b32_e32 v91, 0xffff0000, v41
	v_lshlrev_b32_e32 v92, 16, v42
	v_and_b32_e32 v93, 0xffff0000, v42
	v_lshlrev_b32_e32 v94, 16, v43
	v_and_b32_e32 v95, 0xffff0000, v43
	v_pk_fma_f32 v[152:153], v[88:89], v[198:199], v[152:153]
	v_pk_fma_f32 v[154:155], v[90:91], v[200:201], v[154:155]
	v_pk_fma_f32 v[156:157], v[92:93], v[202:203], v[156:157]
	v_pk_fma_f32 v[158:159], v[94:95], v[204:205], v[158:159]
	v_cvt_pk_bf16_f32 v164, v152, v153
	v_cvt_pk_bf16_f32 v165, v154, v155
	v_cvt_pk_bf16_f32 v166, v156, v157
	v_cvt_pk_bf16_f32 v167, v158, v159
	global_store_dwordx4 v161, v[164:167], s[44:45] nt
	s_add_u32 s44, s44, 0x1000
	s_addc_u32 s45, s45, 0
	s_nop 1
	s_add_u32 s28, s28, 0x1000000
	s_addc_u32 s29, s29, 0
	s_waitcnt vmcnt(8)
; DI u32x4 pack8(const float (&f)[8]) { u32x4 w; w.x = pk2(f[0], f[1]); w.y = pk2(f[2], f[3]); w.z = pk2(f[4], f[5]); w.w = pk2(f[6], f[7]); return w; }
; DI void phase_conv(const Params& p) {
;     ...
;         for (int r = 0; r < 11; ++r) raw[r] = (r >= 3 || t0 > 0) ? *(const u32x4*)(big + (size_t)(tok0 - 3 + r) * 4096 + ch) : (u32x4){0u, 0u, 0u, 0u};
; #pragma unroll
;         for (int o = 0; o < 8; ++o) {
;             float acc[8];
; #pragma unroll
;             for (int e = 0; e < 8; ++e) acc[e] = bs[e];
; #pragma unroll
;             for (int jx = 0; jx < 4; ++jx) { float f[8]; unpack8(raw[o + jx], f);
; #pragma unroll
;                 for (int e = 0; e < 8; ++e) acc[e] += f[e] * wv[jx][e]; }
;             *(u32x4*)(xc + (size_t)(tok0 + o) * DM + ch) = pack8(acc);
	s_cmp_eq_u32 s40, 0
	s_cbranch_scc0 .Lcv_nopad3
	v_mov_b32_e32 v44, 0
	v_mov_b32_e32 v45, 0
	v_mov_b32_e32 v46, 0
	v_mov_b32_e32 v47, 0
	v_mov_b32_e32 v48, 0
	v_mov_b32_e32 v49, 0
	v_mov_b32_e32 v50, 0
	v_mov_b32_e32 v51, 0
	v_mov_b32_e32 v52, 0
	v_mov_b32_e32 v53, 0
	v_mov_b32_e32 v54, 0
	v_mov_b32_e32 v55, 0
.Lcv_nopad3:
	s_mov_b64 s[44:45], s[28:29]
	v_lshlrev_b32_e32 v88, 16, v44
	v_and_b32_e32 v89, 0xffff0000, v44
	v_lshlrev_b32_e32 v90, 16, v45
	v_and_b32_e32 v91, 0xffff0000, v45
	v_lshlrev_b32_e32 v92, 16, v46
	v_and_b32_e32 v93, 0xffff0000, v46
	v_lshlrev_b32_e32 v94, 16, v47
	v_and_b32_e32 v95, 0xffff0000, v47
	v_pk_fma_f32 v[96:97], v[88:89], v[232:233], v[206:207]
	v_pk_fma_f32 v[98:99], v[90:91], v[234:235], v[208:209]
	v_pk_fma_f32 v[100:101], v[92:93], v[236:237], v[210:211]
	v_pk_fma_f32 v[102:103], v[94:95], v[238:239], v[212:213]
	v_lshlrev_b32_e32 v88, 16, v48
	v_and_b32_e32 v89, 0xffff0000, v48
	v_lshlrev_b32_e32 v90, 16, v49
	v_and_b32_e32 v91, 0xffff0000, v49
	v_lshlrev_b32_e32 v92, 16, v50
	v_and_b32_e32 v93, 0xffff0000, v50
	v_lshlrev_b32_e32 v94, 16, v51
	v_and_b32_e32 v95, 0xffff0000, v51
	v_pk_fma_f32 v[96:97], v[88:89], v[240:241], v[96:97]
	v_pk_fma_f32 v[98:99], v[90:91], v[242:243], v[98:99]
	v_pk_fma_f32 v[100:101], v[92:93], v[244:245], v[100:101]
	v_pk_fma_f32 v[102:103], v[94:95], v[246:247], v[102:103]
	v_pk_fma_f32 v[104:105], v[88:89], v[232:233], v[206:207]
	v_pk_fma_f32 v[106:107], v[90:91], v[234:235], v[208:209]
	v_pk_fma_f32 v[108:109], v[92:93], v[236:237], v[210:211]
	v_pk_fma_f32 v[110:111], v[94:95], v[238:239], v[212:213]
	v_lshlrev_b32_e32 v88, 16, v52
	v_and_b32_e32 v89, 0xffff0000, v52
	v_lshlrev_b32_e32 v90, 16, v53
	v_and_b32_e32 v91, 0xffff0000, v53
	v_lshlrev_b32_e32 v92, 16, v54
	v_and_b32_e32 v93, 0xffff0000, v54
	v_lshlrev_b32_e32 v94, 16, v55
	v_and_b32_e32 v95, 0xffff0000, v55
	v_pk_fma_f32 v[96:97], v[88:89], v[248:249], v[96:97]
	v_pk_fma_f32 v[98:99], v[90:91], v[250:251], v[98:99]
	v_pk_fma_f32 v[100:101], v[92:93], v[252:253], v[100:101]
	v_pk_fma_f32 v[102:103], v[94:95], v[254:255], v[102:103]
	v_pk_fma_f32 v[104:105], v[88:89], v[240:241], v[104:105]
	v_pk_fma_f32 v[106:107], v[90:91], v[242:243], v[106:107]
	v_pk_fma_f32 v[108:109], v[92:93], v[244:245], v[108:109]
	v_pk_fma_f32 v[110:111], v[94:95], v[246:247], v[110:111]
	v_pk_fma_f32 v[112:113], v[88:89], v[232:233], v[206:207]
	v_pk_fma_f32 v[114:115], v[90:91], v[234:235], v[208:209]
	v_pk_fma_f32 v[116:117], v[92:93], v[236:237], v[210:211]
	v_pk_fma_f32 v[118:119], v[94:95], v[238:239], v[212:213]
	v_lshlrev_b32_e32 v88, 16, v56
	v_and_b32_e32 v89, 0xffff0000, v56
	v_lshlrev_b32_e32 v90, 16, v57
	v_and_b32_e32 v91, 0xffff0000, v57
	v_lshlrev_b32_e32 v92, 16, v58
	v_and_b32_e32 v93, 0xffff0000, v58
	v_lshlrev_b32_e32 v94, 16, v59
	v_and_b32_e32 v95, 0xffff0000, v59
	v_pk_fma_f32 v[96:97], v[88:89], v[198:199], v[96:97]
	v_pk_fma_f32 v[98:99], v[90:91], v[200:201], v[98:99]
	v_pk_fma_f32 v[100:101], v[92:93], v[202:203], v[100:101]
	v_pk_fma_f32 v[102:103], v[94:95], v[204:205], v[102:103]
	v_pk_fma_f32 v[104:105], v[88:89], v[248:249], v[104:105]
	v_pk_fma_f32 v[106:107], v[90:91], v[250:251], v[106:107]
	v_pk_fma_f32 v[108:109], v[92:93], v[252:253], v[108:109]
	v_pk_fma_f32 v[110:111], v[94:95], v[254:255], v[110:111]
	v_pk_fma_f32 v[112:113], v[88:89], v[240:241], v[112:113]
	v_pk_fma_f32 v[114:115], v[90:91], v[242:243], v[114:115]
	v_pk_fma_f32 v[116:117], v[92:93], v[244:245], v[116:117]
	v_pk_fma_f32 v[118:119], v[94:95], v[246:247], v[118:119]
	v_pk_fma_f32 v[120:121], v[88:89], v[232:233], v[206:207]
	v_pk_fma_f32 v[122:123], v[90:91], v[234:235], v[208:209]
	v_pk_fma_f32 v[124:125], v[92:93], v[236:237], v[210:211]
	v_pk_fma_f32 v[126:127], v[94:95], v[238:239], v[212:213]
	v_cvt_pk_bf16_f32 v164, v96, v97
	v_cvt_pk_bf16_f32 v165, v98, v99
	v_cvt_pk_bf16_f32 v166, v100, v101
	v_cvt_pk_bf16_f32 v167, v102, v103
	global_store_dwordx4 v161, v[164:167], s[44:45] nt
	s_add_u32 s44, s44, 0x1000
	s_addc_u32 s45, s45, 0
	s_nop 1
	v_lshlrev_b32_e32 v88, 16, v60
	v_and_b32_e32 v89, 0xffff0000, v60
	v_lshlrev_b32_e32 v90, 16, v61
	v_and_b32_e32 v91, 0xffff0000, v61
	v_lshlrev_b32_e32 v92, 16, v62
	v_and_b32_e32 v93, 0xffff0000, v62
	v_lshlrev_b32_e32 v94, 16, v63
	v_and_b32_e32 v95, 0xffff0000, v63
	v_pk_fma_f32 v[104:105], v[88:89], v[198:199], v[104:105]
	v_pk_fma_f32 v[106:107], v[90:91], v[200:201], v[106:107]
	v_pk_fma_f32 v[108:109], v[92:93], v[202:203], v[108:109]
	v_pk_fma_f32 v[110:111], v[94:95], v[204:205], v[110:111]
	v_pk_fma_f32 v[112:113], v[88:89], v[248:249], v[112:113]
	v_pk_fma_f32 v[114:115], v[90:91], v[250:251], v[114:115]
	v_pk_fma_f32 v[116:117], v[92:93], v[252:253], v[116:117]
	v_pk_fma_f32 v[118:119], v[94:95], v[254:255], v[118:119]
	v_pk_fma_f32 v[120:121], v[88:89], v[240:241], v[120:121]
	v_pk_fma_f32 v[122:123], v[90:91], v[242:243], v[122:123]
	v_pk_fma_f32 v[124:125], v[92:93], v[244:245], v[124:125]
	v_pk_fma_f32 v[126:127], v[94:95], v[246:247], v[126:127]
	v_pk_fma_f32 v[128:129], v[88:89], v[232:233], v[206:207]
	v_pk_fma_f32 v[130:131], v[90:91], v[234:235], v[208:209]
	v_pk_fma_f32 v[132:133], v[92:93], v[236:237], v[210:211]
	v_pk_fma_f32 v[134:135], v[94:95], v[238:239], v[212:213]
	v_cvt_pk_bf16_f32 v164, v104, v105
	v_cvt_pk_bf16_f32 v165, v106, v107
	v_cvt_pk_bf16_f32 v166, v108, v109
	v_cvt_pk_bf16_f32 v167, v110, v111
	global_store_dwordx4 v161, v[164:167], s[44:45] nt
	s_add_u32 s44, s44, 0x1000
	s_addc_u32 s45, s45, 0
	s_nop 1
	v_lshlrev_b32_e32 v88, 16, v64
	v_and_b32_e32 v89, 0xffff0000, v64
	v_lshlrev_b32_e32 v90, 16, v65
	v_and_b32_e32 v91, 0xffff0000, v65
; DI u32x4 pack8(const float (&f)[8]) { u32x4 w; w.x = pk2(f[0], f[1]); w.y = pk2(f[2], f[3]); w.z = pk2(f[4], f[5]); w.w = pk2(f[6], f[7]); return w; }
; DI void phase_conv(const Params& p) {
;     ...
;         for (int o = 0; o < 8; ++o) {
;             float acc[8];
; #pragma unroll
;             for (int e = 0; e < 8; ++e) acc[e] = bs[e];
; #pragma unroll
;             for (int jx = 0; jx < 4; ++jx) { float f[8]; unpack8(raw[o + jx], f);
; #pragma unroll
;                 for (int e = 0; e < 8; ++e) acc[e] += f[e] * wv[jx][e]; }
;             *(u32x4*)(xc + (size_t)(tok0 + o) * DM + ch) = pack8(acc);
	v_lshlrev_b32_e32 v92, 16, v66
	v_and_b32_e32 v93, 0xffff0000, v66
	v_lshlrev_b32_e32 v94, 16, v67
	v_and_b32_e32 v95, 0xffff0000, v67
	v_pk_fma_f32 v[112:113], v[88:89], v[198:199], v[112:113]
	v_pk_fma_f32 v[114:115], v[90:91], v[200:201], v[114:115]
	v_pk_fma_f32 v[116:117], v[92:93], v[202:203], v[116:117]
	v_pk_fma_f32 v[118:119], v[94:95], v[204:205], v[118:119]
	v_pk_fma_f32 v[120:121], v[88:89], v[248:249], v[120:121]
	v_pk_fma_f32 v[122:123], v[90:91], v[250:251], v[122:123]
	v_pk_fma_f32 v[124:125], v[92:93], v[252:253], v[124:125]
	v_pk_fma_f32 v[126:127], v[94:95], v[254:255], v[126:127]
	v_pk_fma_f32 v[128:129], v[88:89], v[240:241], v[128:129]
	v_pk_fma_f32 v[130:131], v[90:91], v[242:243], v[130:131]
	v_pk_fma_f32 v[132:133], v[92:93], v[244:245], v[132:133]
	v_pk_fma_f32 v[134:135], v[94:95], v[246:247], v[134:135]
	v_pk_fma_f32 v[136:137], v[88:89], v[232:233], v[206:207]
	v_pk_fma_f32 v[138:139], v[90:91], v[234:235], v[208:209]
	v_pk_fma_f32 v[140:141], v[92:93], v[236:237], v[210:211]
	v_pk_fma_f32 v[142:143], v[94:95], v[238:239], v[212:213]
	v_cvt_pk_bf16_f32 v164, v112, v113
	v_cvt_pk_bf16_f32 v165, v114, v115
	v_cvt_pk_bf16_f32 v166, v116, v117
	v_cvt_pk_bf16_f32 v167, v118, v119
	global_store_dwordx4 v161, v[164:167], s[44:45] nt
	s_add_u32 s44, s44, 0x1000
	s_addc_u32 s45, s45, 0
	s_nop 1
	v_lshlrev_b32_e32 v88, 16, v68
	v_and_b32_e32 v89, 0xffff0000, v68
	v_lshlrev_b32_e32 v90, 16, v69
	v_and_b32_e32 v91, 0xffff0000, v69
	v_lshlrev_b32_e32 v92, 16, v70
	v_and_b32_e32 v93, 0xffff0000, v70
	v_lshlrev_b32_e32 v94, 16, v71
	v_and_b32_e32 v95, 0xffff0000, v71
	v_pk_fma_f32 v[120:121], v[88:89], v[198:199], v[120:121]
	v_pk_fma_f32 v[122:123], v[90:91], v[200:201], v[122:123]
	v_pk_fma_f32 v[124:125], v[92:93], v[202:203], v[124:125]
	v_pk_fma_f32 v[126:127], v[94:95], v[204:205], v[126:127]
	v_pk_fma_f32 v[128:129], v[88:89], v[248:249], v[128:129]
	v_pk_fma_f32 v[130:131], v[90:91], v[250:251], v[130:131]
	v_pk_fma_f32 v[132:133], v[92:93], v[252:253], v[132:133]
	v_pk_fma_f32 v[134:135], v[94:95], v[254:255], v[134:135]
	v_pk_fma_f32 v[136:137], v[88:89], v[240:241], v[136:137]
	v_pk_fma_f32 v[138:139], v[90:91], v[242:243], v[138:139]
	v_pk_fma_f32 v[140:141], v[92:93], v[244:245], v[140:141]
	v_pk_fma_f32 v[142:143], v[94:95], v[246:247], v[142:143]
	v_pk_fma_f32 v[144:145], v[88:89], v[232:233], v[206:207]
	v_pk_fma_f32 v[146:147], v[90:91], v[234:235], v[208:209]
	v_pk_fma_f32 v[148:149], v[92:93], v[236:237], v[210:211]
	v_pk_fma_f32 v[150:151], v[94:95], v[238:239], v[212:213]
	v_cvt_pk_bf16_f32 v164, v120, v121
	v_cvt_pk_bf16_f32 v165, v122, v123
	v_cvt_pk_bf16_f32 v166, v124, v125
	v_cvt_pk_bf16_f32 v167, v126, v127
	global_store_dwordx4 v161, v[164:167], s[44:45] nt
	s_add_u32 s44, s44, 0x1000
	s_addc_u32 s45, s45, 0
	s_nop 1
	v_lshlrev_b32_e32 v88, 16, v72
	v_and_b32_e32 v89, 0xffff0000, v72
	v_lshlrev_b32_e32 v90, 16, v73
	v_and_b32_e32 v91, 0xffff0000, v73
	v_lshlrev_b32_e32 v92, 16, v74
	v_and_b32_e32 v93, 0xffff0000, v74
	v_lshlrev_b32_e32 v94, 16, v75
	v_and_b32_e32 v95, 0xffff0000, v75
	v_pk_fma_f32 v[128:129], v[88:89], v[198:199], v[128:129]
	v_pk_fma_f32 v[130:131], v[90:91], v[200:201], v[130:131]
	v_pk_fma_f32 v[132:133], v[92:93], v[202:203], v[132:133]
	v_pk_fma_f32 v[134:135], v[94:95], v[204:205], v[134:135]
	v_pk_fma_f32 v[136:137], v[88:89], v[248:249], v[136:137]
	v_pk_fma_f32 v[138:139], v[90:91], v[250:251], v[138:139]
	v_pk_fma_f32 v[140:141], v[92:93], v[252:253], v[140:141]
	v_pk_fma_f32 v[142:143], v[94:95], v[254:255], v[142:143]
	v_pk_fma_f32 v[144:145], v[88:89], v[240:241], v[144:145]
	v_pk_fma_f32 v[146:147], v[90:91], v[242:243], v[146:147]
; DI u32x4 pack8(const float (&f)[8]) { u32x4 w; w.x = pk2(f[0], f[1]); w.y = pk2(f[2], f[3]); w.z = pk2(f[4], f[5]); w.w = pk2(f[6], f[7]); return w; }
; DI void phase_conv(const Params& p) {
;     ...
;         for (int o = 0; o < 8; ++o) {
;             float acc[8];
; #pragma unroll
;             for (int e = 0; e < 8; ++e) acc[e] = bs[e];
; #pragma unroll
;             for (int jx = 0; jx < 4; ++jx) { float f[8]; unpack8(raw[o + jx], f);
; #pragma unroll
;                 for (int e = 0; e < 8; ++e) acc[e] += f[e] * wv[jx][e]; }
;             *(u32x4*)(xc + (size_t)(tok0 + o) * DM + ch) = pack8(acc);
	v_pk_fma_f32 v[148:149], v[92:93], v[244:245], v[148:149]
	v_pk_fma_f32 v[150:151], v[94:95], v[246:247], v[150:151]
	v_pk_fma_f32 v[152:153], v[88:89], v[232:233], v[206:207]
	v_pk_fma_f32 v[154:155], v[90:91], v[234:235], v[208:209]
	v_pk_fma_f32 v[156:157], v[92:93], v[236:237], v[210:211]
	v_pk_fma_f32 v[158:159], v[94:95], v[238:239], v[212:213]
	v_cvt_pk_bf16_f32 v164, v128, v129
	v_cvt_pk_bf16_f32 v165, v130, v131
	v_cvt_pk_bf16_f32 v166, v132, v133
	v_cvt_pk_bf16_f32 v167, v134, v135
	global_store_dwordx4 v161, v[164:167], s[44:45] nt
	s_add_u32 s44, s44, 0x1000
	s_addc_u32 s45, s45, 0
	s_nop 1
	v_lshlrev_b32_e32 v88, 16, v76
	v_and_b32_e32 v89, 0xffff0000, v76
	v_lshlrev_b32_e32 v90, 16, v77
	v_and_b32_e32 v91, 0xffff0000, v77
	v_lshlrev_b32_e32 v92, 16, v78
	v_and_b32_e32 v93, 0xffff0000, v78
	v_lshlrev_b32_e32 v94, 16, v79
	v_and_b32_e32 v95, 0xffff0000, v79
	v_pk_fma_f32 v[136:137], v[88:89], v[198:199], v[136:137]
	v_pk_fma_f32 v[138:139], v[90:91], v[200:201], v[138:139]
	v_pk_fma_f32 v[140:141], v[92:93], v[202:203], v[140:141]
	v_pk_fma_f32 v[142:143], v[94:95], v[204:205], v[142:143]
	v_pk_fma_f32 v[144:145], v[88:89], v[248:249], v[144:145]
	v_pk_fma_f32 v[146:147], v[90:91], v[250:251], v[146:147]
	v_pk_fma_f32 v[148:149], v[92:93], v[252:253], v[148:149]
	v_pk_fma_f32 v[150:151], v[94:95], v[254:255], v[150:151]
	v_pk_fma_f32 v[152:153], v[88:89], v[240:241], v[152:153]
	v_pk_fma_f32 v[154:155], v[90:91], v[242:243], v[154:155]
	v_pk_fma_f32 v[156:157], v[92:93], v[244:245], v[156:157]
	v_pk_fma_f32 v[158:159], v[94:95], v[246:247], v[158:159]
	v_cvt_pk_bf16_f32 v164, v136, v137
	v_cvt_pk_bf16_f32 v165, v138, v139
	v_cvt_pk_bf16_f32 v166, v140, v141
	v_cvt_pk_bf16_f32 v167, v142, v143
	global_store_dwordx4 v161, v[164:167], s[44:45] nt
	s_add_u32 s44, s44, 0x1000
	s_addc_u32 s45, s45, 0
	s_nop 1
	v_lshlrev_b32_e32 v88, 16, v80
	v_and_b32_e32 v89, 0xffff0000, v80
	v_lshlrev_b32_e32 v90, 16, v81
	v_and_b32_e32 v91, 0xffff0000, v81
	v_lshlrev_b32_e32 v92, 16, v82
	v_and_b32_e32 v93, 0xffff0000, v82
	v_lshlrev_b32_e32 v94, 16, v83
	v_and_b32_e32 v95, 0xffff0000, v83
	v_pk_fma_f32 v[144:145], v[88:89], v[198:199], v[144:145]
	v_pk_fma_f32 v[146:147], v[90:91], v[200:201], v[146:147]
	v_pk_fma_f32 v[148:149], v[92:93], v[202:203], v[148:149]
	v_pk_fma_f32 v[150:151], v[94:95], v[204:205], v[150:151]
	v_pk_fma_f32 v[152:153], v[88:89], v[248:249], v[152:153]
	v_pk_fma_f32 v[154:155], v[90:91], v[250:251], v[154:155]
	v_pk_fma_f32 v[156:157], v[92:93], v[252:253], v[156:157]
	v_pk_fma_f32 v[158:159], v[94:95], v[254:255], v[158:159]
	v_cvt_pk_bf16_f32 v164, v144, v145
	v_cvt_pk_bf16_f32 v165, v146, v147
	v_cvt_pk_bf16_f32 v166, v148, v149
	v_cvt_pk_bf16_f32 v167, v150, v151
	global_store_dwordx4 v161, v[164:167], s[44:45] nt
	s_add_u32 s44, s44, 0x1000
	s_addc_u32 s45, s45, 0
	s_nop 1
	v_lshlrev_b32_e32 v88, 16, v84
	v_and_b32_e32 v89, 0xffff0000, v84
	v_lshlrev_b32_e32 v90, 16, v85
	v_and_b32_e32 v91, 0xffff0000, v85
	v_lshlrev_b32_e32 v92, 16, v86
	v_and_b32_e32 v93, 0xffff0000, v86
	v_lshlrev_b32_e32 v94, 16, v87
	v_and_b32_e32 v95, 0xffff0000, v87
	v_pk_fma_f32 v[152:153], v[88:89], v[198:199], v[152:153]
	v_pk_fma_f32 v[154:155], v[90:91], v[200:201], v[154:155]
	v_pk_fma_f32 v[156:157], v[92:93], v[202:203], v[156:157]
	v_pk_fma_f32 v[158:159], v[94:95], v[204:205], v[158:159]
	v_cvt_pk_bf16_f32 v164, v152, v153
	v_cvt_pk_bf16_f32 v165, v154, v155
	v_cvt_pk_bf16_f32 v166, v156, v157
	v_cvt_pk_bf16_f32 v167, v158, v159
	global_store_dwordx4 v161, v[164:167], s[44:45] nt
	s_add_u32 s44, s44, 0x1000
	s_addc_u32 s45, s45, 0
	s_nop 1
	s_add_u32 s28, s28, 0x1000000
	s_addc_u32 s29, s29, 0
	s_branch .LBB0_884
